# in-proj epilogue: the eight per-row RMS scale loads issued together with counted waits (were load+vmcnt(0)+sqrt chains), on top of cprep hoist + scan rewrite
# speedup vs baseline: 1.0041x; 1.0041x over previous
;     __device__ __forceinline__ void operator()(const f32x4 (&acc)[2][2][4][2], const Unit& u, int wr, int wc, int fr, int fq) const {
;     ...
;             for (int m = 0; m < 4; ++m) scv[ai][m] = rs ? rs[row0 + ai * HALF + m * 16] : 0.f;
; #pragma unroll
;         for (int ai = 0; ai < 2; ++ai)
; #pragma unroll
;             for (int m = 0; m < 4; ++m) scv[ai][m] = rs ? 1.0f / sqrtf(scv[ai][m] * (1.0f / D) + 1e-6f) : 1.0f;
.LBB0_141:
	v_lshl_add_u64 v[160:161], v[144:145], 2, s[18:19]
	s_waitcnt vmcnt(0)
	v_fmamk_f32 v146, v233, 0x3a000000, v212
	v_cmp_gt_f32_e32 vcc, s67, v146
	v_mul_f32_e32 v150, 0x4f800000, v146
	s_nop 0
	v_cndmask_b32_e32 v146, v146, v150, vcc
	v_sqrt_f32_e32 v150, v146
	s_nop 0
	v_add_u32_e32 v154, -1, v150
	v_fma_f32 v158, -v154, v150, v146
	v_cmp_ge_f32_e64 s[4:5], 0, v158
	v_add_u32_e32 v158, 1, v150
	s_nop 0
	v_cndmask_b32_e64 v154, v150, v154, s[4:5]
	v_fma_f32 v150, -v158, v150, v146
	v_cmp_lt_f32_e64 s[4:5], 0, v150
	s_nop 1
	v_cndmask_b32_e64 v150, v154, v158, s[4:5]
	v_mul_f32_e32 v154, 0x37800000, v150
	v_cndmask_b32_e32 v150, v150, v154, vcc
	v_cmp_class_f32_e32 vcc, v146, v213
	s_nop 1
	v_cndmask_b32_e32 v161, v150, v146, vcc

;     __device__ __forceinline__ void operator()(const f32x4 (&acc)[2][2][4][2], const Unit& u, int wr, int wc, int fr, int fq) const {
;     ...
;             for (int m = 0; m < 4; ++m) scv[ai][m] = rs ? rs[row0 + ai * HALF + m * 16] : 0.f;
; #pragma unroll
;         for (int ai = 0; ai < 2; ++ai)
; #pragma unroll
;             for (int m = 0; m < 4; ++m) scv[ai][m] = rs ? 1.0f / sqrtf(scv[ai][m] * (1.0f / D) + 1e-6f) : 1.0f;
.LBB0_149:
	v_lshl_add_u64 v[234:235], v[144:145], 2, s[18:19]
	global_load_dword v226, v[234:235], off
	global_load_dword v227, v[234:235], off offset:64
	global_load_dword v228, v[234:235], off offset:128
	global_load_dword v229, v[234:235], off offset:192
	global_load_dword v230, v[234:235], off offset:512
	global_load_dword v231, v[234:235], off offset:576
	global_load_dword v232, v[234:235], off offset:640
	global_load_dword v233, v[234:235], off offset:704
	v_lshl_add_u64 v[146:147], v[144:145], 2, s[18:19]
	s_waitcnt vmcnt(7)
	v_fmamk_f32 v146, v226, 0x3a000000, v212
	v_cmp_gt_f32_e32 vcc, s67, v146
	v_mul_f32_e32 v147, 0x4f800000, v146
	s_nop 0
	v_cndmask_b32_e32 v146, v146, v147, vcc
	v_sqrt_f32_e32 v147, v146
	s_nop 0
	v_add_u32_e32 v148, -1, v147
	v_fma_f32 v149, -v148, v147, v146
	v_cmp_ge_f32_e64 s[4:5], 0, v149
	v_add_u32_e32 v149, 1, v147
	s_nop 0
	v_cndmask_b32_e64 v148, v147, v148, s[4:5]
	v_fma_f32 v147, -v149, v147, v146
	v_cmp_lt_f32_e64 s[4:5], 0, v147
	s_nop 1
	v_cndmask_b32_e64 v147, v148, v149, s[4:5]
	v_mul_f32_e32 v148, 0x37800000, v147
	v_cndmask_b32_e32 v147, v147, v148, vcc
	v_cmp_class_f32_e32 vcc, v146, v213
	s_nop 1
	v_cndmask_b32_e32 v148, v147, v146, vcc
	s_and_b64 vcc, exec, s[38:39]
	s_cbranch_vccnz .LBB0_134
.LBB0_150:
	v_lshl_add_u64 v[146:147], v[144:145], 2, s[18:19]
	s_waitcnt vmcnt(6)
	v_fmamk_f32 v34, v227, 0x3a000000, v212
	v_cmp_gt_f32_e32 vcc, s67, v34
	v_mul_f32_e32 v146, 0x4f800000, v34
	s_nop 0
	v_cndmask_b32_e32 v34, v34, v146, vcc
	v_sqrt_f32_e32 v146, v34
	s_nop 0
	v_add_u32_e32 v147, -1, v146
	v_fma_f32 v149, -v147, v146, v34
	v_cmp_ge_f32_e64 s[4:5], 0, v149
	v_add_u32_e32 v149, 1, v146
	s_nop 0
	v_cndmask_b32_e64 v147, v146, v147, s[4:5]
	v_fma_f32 v146, -v149, v146, v34
	v_cmp_lt_f32_e64 s[4:5], 0, v146
	s_nop 1
	v_cndmask_b32_e64 v146, v147, v149, s[4:5]
	v_mul_f32_e32 v147, 0x37800000, v146
	v_cndmask_b32_e32 v146, v146, v147, vcc
	v_cmp_class_f32_e32 vcc, v34, v213
	s_nop 1
	v_cndmask_b32_e32 v34, v146, v34, vcc
	v_mov_b32_e32 v147, 0x3a83126f
	s_and_b64 vcc, exec, s[38:39]
	v_mov_b32_e32 v152, 0x3a83126f
	s_cbranch_vccnz .LBB0_135
.LBB0_151:
	v_lshl_add_u64 v[158:159], v[144:145], 2, s[18:19]
	s_waitcnt vmcnt(5)
	v_fmamk_f32 v146, v228, 0x3a000000, v212
	v_cmp_gt_f32_e32 vcc, s67, v146
	v_mul_f32_e32 v149, 0x4f800000, v146
	s_nop 0
	v_cndmask_b32_e32 v146, v146, v149, vcc
	v_sqrt_f32_e32 v149, v146
	s_nop 0
	v_add_u32_e32 v150, -1, v149
	v_fma_f32 v152, -v150, v149, v146
	v_cmp_ge_f32_e64 s[4:5], 0, v152
	v_add_u32_e32 v152, 1, v149
	s_nop 0
	v_cndmask_b32_e64 v150, v149, v150, s[4:5]
	v_fma_f32 v149, -v152, v149, v146
	v_cmp_lt_f32_e64 s[4:5], 0, v149
	s_nop 1
	v_cndmask_b32_e64 v149, v150, v152, s[4:5]
	v_mul_f32_e32 v150, 0x37800000, v149
	v_cndmask_b32_e32 v149, v149, v150, vcc
	v_cmp_class_f32_e32 vcc, v146, v213
	s_nop 1
	v_cndmask_b32_e32 v152, v149, v146, vcc
	s_and_b64 vcc, exec, s[38:39]
	s_cbranch_vccnz .LBB0_136
.LBB0_152:
	v_lshl_add_u64 v[146:147], v[144:145], 2, s[18:19]
	s_waitcnt vmcnt(4)
	v_fmamk_f32 v146, v229, 0x3a000000, v212
	v_cmp_gt_f32_e32 vcc, s67, v146
	v_mul_f32_e32 v147, 0x4f800000, v146
	s_nop 0
	v_cndmask_b32_e32 v146, v146, v147, vcc
	v_sqrt_f32_e32 v147, v146
	s_nop 0
	v_add_u32_e32 v149, -1, v147
	v_fma_f32 v150, -v149, v147, v146
	v_cmp_ge_f32_e64 s[4:5], 0, v150
	v_add_u32_e32 v150, 1, v147
	s_nop 0
	v_cndmask_b32_e64 v149, v147, v149, s[4:5]
	v_fma_f32 v147, -v150, v147, v146
	v_cmp_lt_f32_e64 s[4:5], 0, v147
	s_nop 1
	v_cndmask_b32_e64 v147, v149, v150, s[4:5]
	v_mul_f32_e32 v149, 0x37800000, v147
	v_cndmask_b32_e32 v147, v147, v149, vcc
	v_cmp_class_f32_e32 vcc, v146, v213
	s_nop 1
	v_cndmask_b32_e32 v147, v147, v146, vcc
	v_mov_b32_e32 v149, 0x3a83126f
	s_and_b64 vcc, exec, s[38:39]
	v_mov_b32_e32 v156, 0x3a83126f
	s_cbranch_vccnz .LBB0_137
.LBB0_153:
	v_lshl_add_u64 v[158:159], v[144:145], 2, s[18:19]
	s_waitcnt vmcnt(3)
	v_fmamk_f32 v146, v230, 0x3a000000, v212
	v_cmp_gt_f32_e32 vcc, s67, v146
	v_mul_f32_e32 v150, 0x4f800000, v146
	s_nop 0
	v_cndmask_b32_e32 v146, v146, v150, vcc
	v_sqrt_f32_e32 v150, v146
	s_nop 0
	v_add_u32_e32 v154, -1, v150
	v_fma_f32 v156, -v154, v150, v146
	v_cmp_ge_f32_e64 s[4:5], 0, v156
	v_add_u32_e32 v156, 1, v150
	s_nop 0
	v_cndmask_b32_e64 v154, v150, v154, s[4:5]
	v_fma_f32 v150, -v156, v150, v146
	v_cmp_lt_f32_e64 s[4:5], 0, v150
	s_nop 1
	v_cndmask_b32_e64 v150, v154, v156, s[4:5]
	v_mul_f32_e32 v154, 0x37800000, v150
	v_cndmask_b32_e32 v150, v150, v154, vcc
	v_cmp_class_f32_e32 vcc, v146, v213
	s_nop 1
	v_cndmask_b32_e32 v156, v150, v146, vcc
	s_and_b64 vcc, exec, s[38:39]
	s_cbranch_vccnz .LBB0_138
.LBB0_154:
	v_lshl_add_u64 v[158:159], v[144:145], 2, s[18:19]
	s_waitcnt vmcnt(2)
	v_fmamk_f32 v146, v231, 0x3a000000, v212
	v_cmp_gt_f32_e32 vcc, s67, v146
	v_mul_f32_e32 v149, 0x4f800000, v146
	s_nop 0
	v_cndmask_b32_e32 v146, v146, v149, vcc
	v_sqrt_f32_e32 v149, v146
	s_nop 0
	v_add_u32_e32 v150, -1, v149
	v_fma_f32 v154, -v150, v149, v146
	v_cmp_ge_f32_e64 s[4:5], 0, v154
	v_add_u32_e32 v154, 1, v149
	s_nop 0
	v_cndmask_b32_e64 v150, v149, v150, s[4:5]
	v_fma_f32 v149, -v154, v149, v146
	v_cmp_lt_f32_e64 s[4:5], 0, v149
	s_nop 1
	v_cndmask_b32_e64 v149, v150, v154, s[4:5]
	v_mul_f32_e32 v150, 0x37800000, v149
	v_cndmask_b32_e32 v149, v149, v150, vcc
	v_cmp_class_f32_e32 vcc, v146, v213
	s_nop 1
	v_cndmask_b32_e32 v149, v149, v146, vcc
	s_mov_b64 s[4:5], -1
	s_and_b64 vcc, exec, s[16:17]
	s_cbranch_vccz .LBB0_139
.LBB0_155:
	v_lshl_add_u64 v[158:159], v[144:145], 2, s[18:19]
	s_waitcnt vmcnt(1)
	v_fmamk_f32 v146, v232, 0x3a000000, v212
	v_cmp_gt_f32_e32 vcc, s67, v146
	v_mul_f32_e32 v150, 0x4f800000, v146
	s_nop 0
	v_cndmask_b32_e32 v146, v146, v150, vcc
	v_sqrt_f32_e32 v150, v146
	s_nop 0
	v_add_u32_e32 v154, -1, v150
	v_fma_f32 v158, -v154, v150, v146
	v_cmp_ge_f32_e64 s[4:5], 0, v158
	v_add_u32_e32 v158, 1, v150
	s_nop 0
	v_cndmask_b32_e64 v154, v150, v154, s[4:5]
	v_fma_f32 v150, -v158, v150, v146
	v_cmp_lt_f32_e64 s[4:5], 0, v150
	s_nop 1
	v_cndmask_b32_e64 v150, v154, v158, s[4:5]
	v_mul_f32_e32 v154, 0x37800000, v150
	v_cndmask_b32_e32 v150, v150, v154, vcc
	v_cmp_class_f32_e32 vcc, v146, v213
	s_nop 1
	v_cndmask_b32_e32 v159, v150, v146, vcc
	s_cbranch_execnz .LBB0_140
